# v66 + back-edge rotation (7.11) in the six GEMM K-loops: loop counter/pointer SALU moved ahead of the loop-back barrier
# baseline (speedup 1.0000x reference)
.LBB0_45:
	s_add_i32 s54, s54, 2
	s_add_u32 s8, s8, 0x100
	s_addc_u32 s9, s9, 0
	s_cmp_gt_u32 s54, 13
	s_barrier
	s_cbranch_scc1 .LBB0_50

.LBB0_80:
	s_add_i32 s39, s39, 2
	s_add_u32 s4, s4, 0x100
	s_addc_u32 s5, s5, 0
	s_cmp_gt_u32 s39, 13
	s_barrier
	s_cbranch_scc1 .LBB0_85

.LBB0_186:
	s_add_i32 s5, s5, 2
	s_add_u32 s35, s35, 0x100
	s_addc_u32 s96, s96, 0
	s_add_u32 s8, s8, 0x100
	s_addc_u32 s9, s9, 0
	s_cmp_ge_i32 s5, s3
	s_barrier
	s_cbranch_scc1 .LBB0_191

.LBB0_585:
	s_add_i32 s54, s54, 2
	s_add_u32 s8, s8, 0x100
	s_addc_u32 s9, s9, 0
	s_cmp_gt_u32 s54, 41
	s_barrier
	s_cbranch_scc1 .LBB0_590

.LBB0_625:
	s_add_i32 s17, s17, 2
	s_add_u32 s6, s6, 0x100
	s_addc_u32 s7, s7, 0
	s_cmp_gt_u32 s17, 41
	s_barrier
	s_cbranch_scc1 .LBB0_630

.LBB0_721:
	s_add_i32 s54, s54, 2
	s_add_u32 s6, s6, 0x100
	s_addc_u32 s7, s7, 0
	s_cmp_gt_u32 s54, 13
	s_barrier
	s_cbranch_scc1 .LBB0_726
